# logical block id permuted at entry (panels of all 4 batches on every XCD; a panel's 4 members still share an XCD)
# baseline (speedup 1.0000x reference)
_Z7hyb_fwd4Args:
	s_and_b32 s3, s2, 7
	s_lshl_b32 s3, s3, 3
	s_bfe_u32 s4, s2, 0x30003
	s_or_b32 s3, s3, s4
	s_andn2_b32 s2, s2, 63
	s_or_b32 s2, s2, s3
	s_load_dword s58, s[0:1], 0xa0
	v_readfirstlane_b32 s96, v0
	s_mov_b32 s83, s2
	s_waitcnt lgkmcnt(0)
	s_and_b32 s3, s58, 7
	s_cmp_lg_u32 s3, 0
	s_cbranch_scc1 .LBB0_2
	s_ashr_i32 s4, s2, 31
	s_lshr_b32 s4, s4, 29
	s_add_i32 s4, s2, s4
	s_and_b32 s5, s4, -8
	s_ashr_i32 s3, s58, 3
	s_sub_i32 s5, s2, s5
	s_mul_i32 s3, s3, s5
	s_ashr_i32 s4, s4, 3
	s_add_i32 s83, s3, s4
